# GEMM accumulator zeroing: 128 v_mov_b32 per unit replaced by 64 v_mov_b64 in 13 of 15 GEMM instances
# baseline (speedup 1.0000x reference)
; template <class Epi>
; __device__ __forceinline__ void gemm_phase(LAS unsigned char* lds, const Gemm g, const StaticOrder& S, const Epi& E, const int wid) {
;     ...
;         const bool has_next = S.next(ui + 1, nxt);
;         const char* nA = has_next ? (const char*)g.A + (size_t)nxt.pm * tsA : cA; const char* nB = has_next ? (const char*)g.Bt + (size_t)nxt.pn * tsB : cB;
;     ...
; #pragma unroll
;         for (int a = 0; a < 2; ++a)
; #pragma unroll
;             for (int b = 0; b < 2; ++b)
; #pragma unroll
;                 for (int m = 0; m < 4; ++m)
; #pragma unroll
;                     for (int n = 0; n < 2; ++n) acc[a][b][m][n] = (f32x4){0.f, 0.f, 0.f, 0.f};
.LBB0_190:
	s_ashr_i32 s27, s26, 31
	s_lshl_b64 s[28:29], s[26:27], 19
	s_add_u32 s28, s42, s28
	s_addc_u32 s29, s43, s29
	s_and_b64 s[30:31], s[0:1], exec
	s_cselect_b32 s27, s29, s51
	s_cselect_b32 s89, s28, s50
	s_ashr_i32 s25, s24, 31
	s_lshl_b64 s[30:31], s[24:25], 19
	s_add_u32 s30, s60, s30
	s_addc_u32 s31, s61, s31
	s_and_b64 s[62:63], s[0:1], exec
	s_cselect_b32 s25, s31, s35
	s_cselect_b32 s94, s30, s34
	s_add_u32 s95, s34, 0x100
	s_addc_u32 s96, s35, 0
	s_add_u32 s34, s50, 0x40080
	v_mov_b64_e32 v[0:1], 0
	s_addc_u32 s35, s51, 0
	s_mov_b32 s97, -2
	v_mov_b64_e32 v[2:3], 0
	v_mov_b64_e32 v[4:5], 0
	v_mov_b64_e32 v[6:7], 0
	v_mov_b64_e32 v[16:17], 0
	v_mov_b64_e32 v[18:19], 0
	v_mov_b64_e32 v[20:21], 0
	v_mov_b64_e32 v[22:23], 0
	v_mov_b64_e32 v[32:33], 0
	v_mov_b64_e32 v[34:35], 0
	v_mov_b64_e32 v[36:37], 0
	v_mov_b64_e32 v[38:39], 0
	v_mov_b64_e32 v[48:49], 0
	v_mov_b64_e32 v[50:51], 0
	v_mov_b64_e32 v[52:53], 0
	v_mov_b64_e32 v[54:55], 0
	v_mov_b64_e32 v[8:9], 0
	v_mov_b64_e32 v[10:11], 0
	v_mov_b64_e32 v[12:13], 0
	v_mov_b64_e32 v[14:15], 0
	v_mov_b64_e32 v[24:25], 0
	v_mov_b64_e32 v[26:27], 0
	v_mov_b64_e32 v[28:29], 0
	v_mov_b64_e32 v[30:31], 0
	v_mov_b64_e32 v[40:41], 0
	v_mov_b64_e32 v[42:43], 0
	v_mov_b64_e32 v[44:45], 0
	v_mov_b64_e32 v[46:47], 0
	v_mov_b64_e32 v[56:57], 0
	v_mov_b64_e32 v[58:59], 0
	v_mov_b64_e32 v[60:61], 0
	v_mov_b64_e32 v[62:63], 0
	v_mov_b64_e32 v[64:65], 0
	v_mov_b64_e32 v[66:67], 0
	v_mov_b64_e32 v[72:73], 0
	v_mov_b64_e32 v[74:75], 0
	v_mov_b64_e32 v[76:77], 0
	v_mov_b64_e32 v[78:79], 0
	v_mov_b64_e32 v[80:81], 0
	v_mov_b64_e32 v[82:83], 0
	v_mov_b64_e32 v[96:97], 0
	v_mov_b64_e32 v[98:99], 0
	v_mov_b64_e32 v[100:101], 0
	v_mov_b64_e32 v[102:103], 0
	v_mov_b64_e32 v[108:109], 0
	v_mov_b64_e32 v[110:111], 0
	v_mov_b64_e32 v[112:113], 0
	v_mov_b64_e32 v[114:115], 0
	v_mov_b64_e32 v[68:69], 0
	v_mov_b64_e32 v[70:71], 0
	v_mov_b64_e32 v[84:85], 0
	v_mov_b64_e32 v[86:87], 0
	v_mov_b64_e32 v[88:89], 0
	v_mov_b64_e32 v[90:91], 0
	v_mov_b64_e32 v[92:93], 0
	v_mov_b64_e32 v[94:95], 0
	v_mov_b64_e32 v[104:105], 0
	v_mov_b64_e32 v[106:107], 0
	v_mov_b64_e32 v[116:117], 0
	v_mov_b64_e32 v[118:119], 0
	v_mov_b64_e32 v[120:121], 0
	v_mov_b64_e32 v[122:123], 0
	v_mov_b64_e32 v[124:125], 0
	v_mov_b64_e32 v[126:127], 0

; template <class Epi>
; __device__ __forceinline__ void gemm_phase(LAS unsigned char* lds, const Gemm g, const StaticOrder& S, const Epi& E, const int wid) {
;     ...
;         const bool has_next = S.next(ui + 1, nxt);
;         const char* nA = has_next ? (const char*)g.A + (size_t)nxt.pm * tsA : cA; const char* nB = has_next ? (const char*)g.Bt + (size_t)nxt.pn * tsB : cB;
;     ...
; #pragma unroll
;         for (int a = 0; a < 2; ++a)
; #pragma unroll
;             for (int b = 0; b < 2; ++b)
; #pragma unroll
;                 for (int m = 0; m < 4; ++m)
; #pragma unroll
;                     for (int n = 0; n < 2; ++n) acc[a][b][m][n] = (f32x4){0.f, 0.f, 0.f, 0.f};
.LBB0_484:
	s_ashr_i32 s27, s26, 31
	s_lshl_b64 s[4:5], s[26:27], 19
	s_add_u32 s28, s42, s4
	s_addc_u32 s29, s43, s5
	s_and_b64 s[4:5], s[6:7], exec
	s_cselect_b32 s27, s29, s39
	s_cselect_b32 s92, s28, s38
	s_ashr_i32 s25, s24, 31
	s_lshl_b64 s[4:5], s[24:25], 19
	s_add_u32 s30, s63, s4
	s_addc_u32 s31, s64, s5
	s_and_b64 s[4:5], s[6:7], exec
	s_cselect_b32 s25, s31, s37
	s_cselect_b32 s93, s30, s36
	s_add_u32 s94, s36, 0x100
	s_addc_u32 s95, s37, 0
	s_add_u32 s36, s38, 0x40080
	v_mov_b64_e32 v[0:1], 0
	s_addc_u32 s37, s39, 0
	s_mov_b32 s96, -2
	v_mov_b64_e32 v[2:3], 0
	v_mov_b64_e32 v[4:5], 0
	v_mov_b64_e32 v[6:7], 0
	v_mov_b64_e32 v[16:17], 0
	v_mov_b64_e32 v[18:19], 0
	v_mov_b64_e32 v[20:21], 0
	v_mov_b64_e32 v[22:23], 0
	v_mov_b64_e32 v[32:33], 0
	v_mov_b64_e32 v[34:35], 0
	v_mov_b64_e32 v[36:37], 0
	v_mov_b64_e32 v[38:39], 0
	v_mov_b64_e32 v[48:49], 0
	v_mov_b64_e32 v[50:51], 0
	v_mov_b64_e32 v[52:53], 0
	v_mov_b64_e32 v[54:55], 0
	v_mov_b64_e32 v[8:9], 0
	v_mov_b64_e32 v[10:11], 0
	v_mov_b64_e32 v[12:13], 0
	v_mov_b64_e32 v[14:15], 0
	v_mov_b64_e32 v[24:25], 0
	v_mov_b64_e32 v[26:27], 0
	v_mov_b64_e32 v[28:29], 0
	v_mov_b64_e32 v[30:31], 0
	v_mov_b64_e32 v[40:41], 0
	v_mov_b64_e32 v[42:43], 0
	v_mov_b64_e32 v[44:45], 0
	v_mov_b64_e32 v[46:47], 0
	v_mov_b64_e32 v[56:57], 0
	v_mov_b64_e32 v[58:59], 0
	v_mov_b64_e32 v[60:61], 0
	v_mov_b64_e32 v[62:63], 0
	v_mov_b64_e32 v[64:65], 0
	v_mov_b64_e32 v[66:67], 0
	v_mov_b64_e32 v[68:69], 0
	v_mov_b64_e32 v[70:71], 0
	v_mov_b64_e32 v[80:81], 0
	v_mov_b64_e32 v[82:83], 0
	v_mov_b64_e32 v[84:85], 0
	v_mov_b64_e32 v[86:87], 0
	v_mov_b64_e32 v[96:97], 0
	v_mov_b64_e32 v[98:99], 0
	v_mov_b64_e32 v[100:101], 0
	v_mov_b64_e32 v[102:103], 0
	v_mov_b64_e32 v[112:113], 0
	v_mov_b64_e32 v[114:115], 0
	v_mov_b64_e32 v[116:117], 0
	v_mov_b64_e32 v[118:119], 0
	v_mov_b64_e32 v[72:73], 0
	v_mov_b64_e32 v[74:75], 0
	v_mov_b64_e32 v[76:77], 0
	v_mov_b64_e32 v[78:79], 0
	v_mov_b64_e32 v[88:89], 0
	v_mov_b64_e32 v[90:91], 0
	v_mov_b64_e32 v[92:93], 0
	v_mov_b64_e32 v[94:95], 0
	v_mov_b64_e32 v[104:105], 0
	v_mov_b64_e32 v[106:107], 0
	v_mov_b64_e32 v[108:109], 0
	v_mov_b64_e32 v[110:111], 0
	v_mov_b64_e32 v[120:121], 0
	v_mov_b64_e32 v[122:123], 0
	v_mov_b64_e32 v[124:125], 0
	v_mov_b64_e32 v[126:127], 0

; template <class Epi>
; __device__ __forceinline__ void gemm_phase(LAS unsigned char* lds, const Gemm g, const StaticOrder& S, const Epi& E, const int wid) {
;     ...
;         const bool has_next = S.next(ui + 1, nxt);
;         const char* nA = has_next ? (const char*)g.A + (size_t)nxt.pm * tsA : cA; const char* nB = has_next ? (const char*)g.Bt + (size_t)nxt.pn * tsB : cB;
;     ...
; #pragma unroll
;         for (int a = 0; a < 2; ++a)
; #pragma unroll
;             for (int b = 0; b < 2; ++b)
; #pragma unroll
;                 for (int m = 0; m < 4; ++m)
; #pragma unroll
;                     for (int n = 0; n < 2; ++n) acc[a][b][m][n] = (f32x4){0.f, 0.f, 0.f, 0.f};
.LBB0_554:
	s_ashr_i32 s21, s20, 31
	s_lshl_b64 s[4:5], s[20:21], 21
	s_add_u32 s22, s44, s4
	s_addc_u32 s23, s45, s5
	s_and_b64 s[4:5], s[6:7], exec
	s_cselect_b32 s1, s23, s31
	s_cselect_b32 s21, s22, s30
	s_ashr_i32 s19, s18, 31
	s_lshl_b64 s[4:5], s[18:19], 21
	s_add_u32 s24, s36, s4
	s_addc_u32 s25, s37, s5
	s_and_b64 s[4:5], s[6:7], exec
	s_cselect_b32 s19, s25, s29
	s_cselect_b32 s78, s24, s28
	s_add_u32 s79, s28, 0x100
	s_addc_u32 s80, s29, 0
	s_add_u32 s28, s30, 0x100080
	v_mov_b32_e32 v0, 0
	s_addc_u32 s29, s31, 0
	s_mov_b32 s81, -2
	v_mov_b32_e32 v1, v0
	v_mov_b64_e32 v[2:3], 0
	v_mov_b64_e32 v[4:5], 0
	v_mov_b64_e32 v[6:7], 0
	v_mov_b64_e32 v[16:17], 0
	v_mov_b64_e32 v[18:19], 0
	v_mov_b64_e32 v[20:21], 0
	v_mov_b64_e32 v[22:23], 0
	v_mov_b64_e32 v[32:33], 0
	v_mov_b64_e32 v[34:35], 0
	v_mov_b64_e32 v[36:37], 0
	v_mov_b64_e32 v[38:39], 0
	v_mov_b64_e32 v[48:49], 0
	v_mov_b64_e32 v[50:51], 0
	v_mov_b64_e32 v[52:53], 0
	v_mov_b64_e32 v[54:55], 0
	v_mov_b64_e32 v[8:9], 0
	v_mov_b64_e32 v[10:11], 0
	v_mov_b64_e32 v[12:13], 0
	v_mov_b64_e32 v[14:15], 0
	v_mov_b64_e32 v[24:25], 0
	v_mov_b64_e32 v[26:27], 0
	v_mov_b64_e32 v[28:29], 0
	v_mov_b64_e32 v[30:31], 0
	v_mov_b64_e32 v[40:41], 0
	v_mov_b64_e32 v[42:43], 0
	v_mov_b64_e32 v[44:45], 0
	v_mov_b64_e32 v[46:47], 0
	v_mov_b64_e32 v[56:57], 0
	v_mov_b64_e32 v[58:59], 0
	v_mov_b64_e32 v[60:61], 0
	v_mov_b64_e32 v[62:63], 0
	v_mov_b64_e32 v[64:65], 0
	v_mov_b64_e32 v[66:67], 0
	v_mov_b64_e32 v[68:69], 0
	v_mov_b64_e32 v[70:71], 0
	v_mov_b64_e32 v[80:81], 0
	v_mov_b64_e32 v[82:83], 0
	v_mov_b64_e32 v[84:85], 0
	v_mov_b64_e32 v[86:87], 0
	v_mov_b64_e32 v[96:97], 0
	v_mov_b64_e32 v[98:99], 0
	v_mov_b64_e32 v[100:101], 0
	v_mov_b64_e32 v[102:103], 0
	v_mov_b64_e32 v[112:113], 0
	v_mov_b64_e32 v[114:115], 0
	v_mov_b64_e32 v[116:117], 0
	v_mov_b64_e32 v[118:119], 0
	v_mov_b64_e32 v[72:73], 0
	v_mov_b64_e32 v[74:75], 0
	v_mov_b64_e32 v[76:77], 0
	v_mov_b64_e32 v[78:79], 0
	v_mov_b64_e32 v[88:89], 0
	v_mov_b64_e32 v[90:91], 0
	v_mov_b64_e32 v[92:93], 0
	v_mov_b64_e32 v[94:95], 0
	v_mov_b64_e32 v[104:105], 0
	v_mov_b64_e32 v[106:107], 0
	v_mov_b64_e32 v[108:109], 0
	v_mov_b64_e32 v[110:111], 0
	v_mov_b64_e32 v[120:121], 0
	v_mov_b64_e32 v[122:123], 0
	v_mov_b64_e32 v[128:129], 0
	v_mov_b64_e32 v[130:131], 0

; template <class Epi>
; __device__ __forceinline__ void gemm_phase(LAS unsigned char* lds, const Gemm g, const StaticOrder& S, const Epi& E, const int wid) {
;     ...
;         const bool has_next = S.next(ui + 1, nxt);
;         const char* nA = has_next ? (const char*)g.A + (size_t)nxt.pm * tsA : cA; const char* nB = has_next ? (const char*)g.Bt + (size_t)nxt.pn * tsB : cB;
;     ...
; #pragma unroll
;         for (int a = 0; a < 2; ++a)
; #pragma unroll
;             for (int b = 0; b < 2; ++b)
; #pragma unroll
;                 for (int m = 0; m < 4; ++m)
; #pragma unroll
;                     for (int n = 0; n < 2; ++n) acc[a][b][m][n] = (f32x4){0.f, 0.f, 0.f, 0.f};
.LBB0_638:
	s_ashr_i32 s21, s20, 31
	s_lshl_b64 s[4:5], s[20:21], 17
	s_add_u32 s24, s58, s4
	s_addc_u32 s25, s59, s5
	s_and_b64 s[4:5], s[6:7], exec
	s_cselect_b32 s21, s25, s27
	s_cselect_b32 s94, s24, s26
	s_ashr_i32 s17, s16, 31
	s_lshl_b64 s[4:5], s[16:17], 17
	s_add_u32 s28, s75, s4
	s_addc_u32 s29, s76, s5
	s_and_b64 s[4:5], s[6:7], exec
	v_mov_b64_e32 v[0:1], 0
	s_cselect_b32 s17, s29, s23
	s_cselect_b32 s95, s28, s22
	s_mov_b64 s[36:37], 0
	s_mov_b64 s[30:31], -1
	s_mov_b64 s[34:35], 0
	v_mov_b64_e32 v[2:3], 0
	v_mov_b64_e32 v[4:5], 0
	v_mov_b64_e32 v[6:7], 0
	v_mov_b64_e32 v[8:9], 0
	v_mov_b64_e32 v[10:11], 0
	v_mov_b64_e32 v[12:13], 0
	v_mov_b64_e32 v[14:15], 0
	v_mov_b64_e32 v[24:25], 0
	v_mov_b64_e32 v[26:27], 0
	v_mov_b64_e32 v[28:29], 0
	v_mov_b64_e32 v[30:31], 0
	v_mov_b64_e32 v[40:41], 0
	v_mov_b64_e32 v[42:43], 0
	v_mov_b64_e32 v[44:45], 0
	v_mov_b64_e32 v[46:47], 0
	v_mov_b64_e32 v[16:17], 0
	v_mov_b64_e32 v[18:19], 0
	v_mov_b64_e32 v[20:21], 0
	v_mov_b64_e32 v[22:23], 0
	v_mov_b64_e32 v[32:33], 0
	v_mov_b64_e32 v[34:35], 0
	v_mov_b64_e32 v[36:37], 0
	v_mov_b64_e32 v[38:39], 0
	v_mov_b64_e32 v[48:49], 0
	v_mov_b64_e32 v[50:51], 0
	v_mov_b64_e32 v[52:53], 0
	v_mov_b64_e32 v[54:55], 0
	v_mov_b64_e32 v[56:57], 0
	v_mov_b64_e32 v[58:59], 0
	v_mov_b64_e32 v[60:61], 0
	v_mov_b64_e32 v[62:63], 0
	v_mov_b64_e32 v[64:65], 0
	v_mov_b64_e32 v[66:67], 0
	v_mov_b64_e32 v[68:69], 0
	v_mov_b64_e32 v[70:71], 0
	v_mov_b64_e32 v[72:73], 0
	v_mov_b64_e32 v[74:75], 0
	v_mov_b64_e32 v[76:77], 0
	v_mov_b64_e32 v[78:79], 0
	v_mov_b64_e32 v[88:89], 0
	v_mov_b64_e32 v[90:91], 0
	v_mov_b64_e32 v[92:93], 0
	v_mov_b64_e32 v[94:95], 0
	v_mov_b64_e32 v[104:105], 0
	v_mov_b64_e32 v[106:107], 0
	v_mov_b64_e32 v[108:109], 0
	v_mov_b64_e32 v[110:111], 0
	v_mov_b64_e32 v[80:81], 0
	v_mov_b64_e32 v[82:83], 0
	v_mov_b64_e32 v[84:85], 0
	v_mov_b64_e32 v[86:87], 0
	v_mov_b64_e32 v[96:97], 0
	v_mov_b64_e32 v[98:99], 0
	v_mov_b64_e32 v[100:101], 0
	v_mov_b64_e32 v[102:103], 0
	v_mov_b64_e32 v[112:113], 0
	v_mov_b64_e32 v[114:115], 0
	v_mov_b64_e32 v[116:117], 0
	v_mov_b64_e32 v[118:119], 0
	v_mov_b64_e32 v[120:121], 0
	v_mov_b64_e32 v[122:123], 0
	v_mov_b64_e32 v[124:125], 0
	v_mov_b64_e32 v[126:127], 0

; template <class Epi>
; __device__ __forceinline__ void gemm_phase(LAS unsigned char* lds, const Gemm g, const StaticOrder& S, const Epi& E, const int wid) {
;     ...
;         const bool has_next = S.next(ui + 1, nxt);
;         const char* nA = has_next ? (const char*)g.A + (size_t)nxt.pm * tsA : cA; const char* nB = has_next ? (const char*)g.Bt + (size_t)nxt.pn * tsB : cB;
;     ...
; #pragma unroll
;         for (int a = 0; a < 2; ++a)
; #pragma unroll
;             for (int b = 0; b < 2; ++b)
; #pragma unroll
;                 for (int m = 0; m < 4; ++m)
; #pragma unroll
;                     for (int n = 0; n < 2; ++n) acc[a][b][m][n] = (f32x4){0.f, 0.f, 0.f, 0.f};
.LBB0_664:
	s_ashr_i32 s23, s22, 31
	s_lshl_b64 s[4:5], s[22:23], 19
	s_add_u32 s24, s42, s4
	s_addc_u32 s25, s43, s5
	s_and_b64 s[4:5], s[6:7], exec
	s_cselect_b32 s9, s25, s31
	s_cselect_b32 s11, s24, s30
	s_ashr_i32 s21, s20, 31
	s_lshl_b64 s[4:5], s[20:21], 19
	s_add_u32 s26, s36, s4
	s_addc_u32 s27, s37, s5
	s_and_b64 s[4:5], s[6:7], exec
	s_cselect_b32 s21, s27, s29
	s_cselect_b32 s23, s26, s28
	s_add_u32 s79, s28, 0x100
	s_addc_u32 s80, s29, 0
	s_add_u32 s28, s30, 0x40080
	v_mov_b32_e32 v0, 0
	s_addc_u32 s29, s31, 0
	s_mov_b32 s81, -2
	s_waitcnt lgkmcnt(0)
	v_mov_b32_e32 v1, v0
	v_mov_b64_e32 v[2:3], 0
	v_mov_b64_e32 v[4:5], 0
	v_mov_b64_e32 v[6:7], 0
	v_mov_b64_e32 v[16:17], 0
	v_mov_b64_e32 v[18:19], 0
	v_mov_b64_e32 v[20:21], 0
	v_mov_b64_e32 v[22:23], 0
	v_mov_b64_e32 v[32:33], 0
	v_mov_b64_e32 v[34:35], 0
	v_mov_b64_e32 v[36:37], 0
	v_mov_b64_e32 v[38:39], 0
	v_mov_b64_e32 v[48:49], 0
	v_mov_b64_e32 v[50:51], 0
	v_mov_b64_e32 v[52:53], 0
	v_mov_b64_e32 v[54:55], 0
	v_mov_b64_e32 v[8:9], 0
	v_mov_b64_e32 v[10:11], 0
	v_mov_b64_e32 v[12:13], 0
	v_mov_b64_e32 v[14:15], 0
	v_mov_b64_e32 v[24:25], 0
	v_mov_b64_e32 v[26:27], 0
	v_mov_b64_e32 v[28:29], 0
	v_mov_b64_e32 v[30:31], 0
	v_mov_b64_e32 v[40:41], 0
	v_mov_b64_e32 v[42:43], 0
	v_mov_b64_e32 v[44:45], 0
	v_mov_b64_e32 v[46:47], 0
	v_mov_b64_e32 v[56:57], 0
	v_mov_b64_e32 v[58:59], 0
	v_mov_b64_e32 v[60:61], 0
	v_mov_b64_e32 v[62:63], 0
	v_mov_b64_e32 v[64:65], 0
	v_mov_b64_e32 v[66:67], 0
	v_mov_b64_e32 v[68:69], 0
	v_mov_b64_e32 v[70:71], 0
	v_mov_b64_e32 v[80:81], 0
	v_mov_b64_e32 v[82:83], 0
	v_mov_b64_e32 v[84:85], 0
	v_mov_b64_e32 v[86:87], 0
	v_mov_b64_e32 v[96:97], 0
	v_mov_b64_e32 v[98:99], 0
	v_mov_b64_e32 v[100:101], 0
	v_mov_b64_e32 v[102:103], 0
	v_mov_b64_e32 v[112:113], 0
	v_mov_b64_e32 v[114:115], 0
	v_mov_b64_e32 v[116:117], 0
	v_mov_b64_e32 v[118:119], 0
	v_mov_b64_e32 v[72:73], 0
	v_mov_b64_e32 v[74:75], 0
	v_mov_b64_e32 v[76:77], 0
	v_mov_b64_e32 v[78:79], 0
	v_mov_b64_e32 v[88:89], 0
	v_mov_b64_e32 v[90:91], 0
	v_mov_b64_e32 v[92:93], 0
	v_mov_b64_e32 v[94:95], 0
	v_mov_b64_e32 v[104:105], 0
	v_mov_b64_e32 v[106:107], 0
	v_mov_b64_e32 v[108:109], 0
	v_mov_b64_e32 v[110:111], 0
	v_mov_b64_e32 v[120:121], 0
	v_mov_b64_e32 v[122:123], 0
	v_mov_b64_e32 v[124:125], 0
	v_mov_b64_e32 v[126:127], 0

; template <class Epi>
; __device__ __forceinline__ void gemm_phase(LAS unsigned char* lds, const Gemm g, const StaticOrder& S, const Epi& E, const int wid) {
;     ...
;         const bool has_next = S.next(ui + 1, nxt);
;         const char* nA = has_next ? (const char*)g.A + (size_t)nxt.pm * tsA : cA; const char* nB = has_next ? (const char*)g.Bt + (size_t)nxt.pn * tsB : cB;
; #pragma unroll 1
;         for (int t = 0; t < nt; t += 2) {
;             const bool last = (t == nt - 2);
;             const char* a1 = cA + (size_t)(t + 1) * kstep;
;             const char* a2 = last ? nA : cA + (size_t)(t + 2) * kstep; const char* b2 = last ? nB : cB + (size_t)(t + 2) * kstep;
;             const char* a3 = a2 + kstep; const char* b3 = b2 + kstep;
;     ...
; #pragma unroll
;         for (int a = 0; a < 2; ++a)
; #pragma unroll
;             for (int b = 0; b < 2; ++b)
; #pragma unroll
;                 for (int m = 0; m < 4; ++m)
; #pragma unroll
;                     for (int n = 0; n < 2; ++n) acc[a][b][m][n] = (f32x4){0.f, 0.f, 0.f, 0.f};
.LBB0_774:
	s_ashr_i32 s25, s24, 31
	s_lshl_b64 s[4:5], s[24:25], 19
	s_add_u32 s26, s52, s4
	s_addc_u32 s27, s53, s5
	s_and_b64 s[4:5], s[6:7], exec
	s_cselect_b32 s1, s27, s31
	s_cselect_b32 s25, s26, s30
	s_ashr_i32 s23, s22, 31
	s_lshl_b64 s[4:5], s[22:23], 19
	s_add_u32 s28, s38, s4
	s_addc_u32 s29, s39, s5
	s_and_b64 s[4:5], s[6:7], exec
	s_cselect_b32 s23, s29, s35
	s_cselect_b32 s83, s28, s34
	s_add_u32 s30, s30, 0x40080
	s_addc_u32 s31, s31, 0
	s_add_u32 s89, s34, 0x100
	v_mov_b32_e32 v0, 0
	s_addc_u32 s90, s35, 0
	s_mov_b32 s91, -2
	s_waitcnt lgkmcnt(0)
	v_mov_b32_e32 v1, v0
	v_mov_b64_e32 v[2:3], 0
	v_mov_b64_e32 v[4:5], 0
	v_mov_b64_e32 v[6:7], 0
	v_mov_b64_e32 v[16:17], 0
	v_mov_b64_e32 v[18:19], 0
	v_mov_b64_e32 v[20:21], 0
	v_mov_b64_e32 v[22:23], 0
	v_mov_b64_e32 v[32:33], 0
	v_mov_b64_e32 v[34:35], 0
	v_mov_b64_e32 v[36:37], 0
	v_mov_b64_e32 v[38:39], 0
	v_mov_b64_e32 v[48:49], 0
	v_mov_b64_e32 v[50:51], 0
	v_mov_b64_e32 v[52:53], 0
	v_mov_b64_e32 v[54:55], 0
	v_mov_b64_e32 v[8:9], 0
	v_mov_b64_e32 v[10:11], 0
	v_mov_b64_e32 v[12:13], 0
	v_mov_b64_e32 v[14:15], 0
	v_mov_b64_e32 v[24:25], 0
	v_mov_b64_e32 v[26:27], 0
	v_mov_b64_e32 v[28:29], 0
	v_mov_b64_e32 v[30:31], 0
	v_mov_b64_e32 v[40:41], 0
	v_mov_b64_e32 v[42:43], 0
	v_mov_b64_e32 v[44:45], 0
	v_mov_b64_e32 v[46:47], 0
	v_mov_b64_e32 v[56:57], 0
	v_mov_b64_e32 v[58:59], 0
	v_mov_b64_e32 v[60:61], 0
	v_mov_b64_e32 v[62:63], 0
	v_mov_b64_e32 v[64:65], 0
	v_mov_b64_e32 v[66:67], 0
	v_mov_b64_e32 v[68:69], 0
	v_mov_b64_e32 v[70:71], 0
	v_mov_b64_e32 v[80:81], 0
	v_mov_b64_e32 v[82:83], 0
	v_mov_b64_e32 v[84:85], 0
	v_mov_b64_e32 v[86:87], 0
	v_mov_b64_e32 v[96:97], 0
	v_mov_b64_e32 v[98:99], 0
	v_mov_b64_e32 v[100:101], 0
	v_mov_b64_e32 v[102:103], 0
	v_mov_b64_e32 v[112:113], 0
	v_mov_b64_e32 v[114:115], 0
	v_mov_b64_e32 v[116:117], 0
	v_mov_b64_e32 v[118:119], 0
	v_mov_b64_e32 v[72:73], 0
	v_mov_b64_e32 v[74:75], 0
	v_mov_b64_e32 v[76:77], 0
	v_mov_b64_e32 v[78:79], 0
	v_mov_b64_e32 v[88:89], 0
	v_mov_b64_e32 v[90:91], 0
	v_mov_b64_e32 v[92:93], 0
	v_mov_b64_e32 v[94:95], 0
	v_mov_b64_e32 v[104:105], 0
	v_mov_b64_e32 v[106:107], 0
	v_mov_b64_e32 v[108:109], 0
	v_mov_b64_e32 v[110:111], 0
	v_mov_b64_e32 v[120:121], 0
	v_mov_b64_e32 v[122:123], 0
	v_mov_b64_e32 v[124:125], 0
	v_mov_b64_e32 v[126:127], 0

; template <class Epi>
; __device__ __forceinline__ void gemm_phase(LAS unsigned char* lds, const Gemm g, const StaticOrder& S, const Epi& E, const int wid) {
;     ...
;             const char* a2 = last ? nA : cA + (size_t)(t + 2) * kstep; const char* b2 = last ? nB : cB + (size_t)(t + 2) * kstep;
;             const char* a3 = a2 + kstep; const char* b3 = b2 + kstep;
;     ...
; #pragma unroll
;         for (int a = 0; a < 2; ++a)
; #pragma unroll
;             for (int b = 0; b < 2; ++b)
; #pragma unroll
;                 for (int m = 0; m < 4; ++m)
; #pragma unroll
;                     for (int n = 0; n < 2; ++n) acc[a][b][m][n] = (f32x4){0.f, 0.f, 0.f, 0.f};
.LBB0_870:
	s_add_u32 s79, s22, 0x100
	v_mov_b64_e32 v[0:1], 0
	s_addc_u32 s80, s23, 0
	s_mov_b32 s81, -2
	v_mov_b64_e32 v[2:3], 0
	v_mov_b64_e32 v[4:5], 0
	v_mov_b64_e32 v[6:7], 0
	v_mov_b64_e32 v[8:9], 0
	v_mov_b64_e32 v[10:11], 0
	v_mov_b64_e32 v[12:13], 0
	v_mov_b64_e32 v[14:15], 0
	v_mov_b64_e32 v[24:25], 0
	v_mov_b64_e32 v[26:27], 0
	v_mov_b64_e32 v[28:29], 0
	v_mov_b64_e32 v[30:31], 0
	v_mov_b64_e32 v[40:41], 0
	v_mov_b64_e32 v[42:43], 0
	v_mov_b64_e32 v[44:45], 0
	v_mov_b64_e32 v[46:47], 0
	v_mov_b64_e32 v[16:17], 0
	v_mov_b64_e32 v[18:19], 0
	v_mov_b64_e32 v[20:21], 0
	v_mov_b64_e32 v[22:23], 0
	v_mov_b64_e32 v[32:33], 0
	v_mov_b64_e32 v[34:35], 0
	v_mov_b64_e32 v[36:37], 0
	v_mov_b64_e32 v[38:39], 0
	v_mov_b64_e32 v[48:49], 0
	v_mov_b64_e32 v[50:51], 0
	v_mov_b64_e32 v[52:53], 0
	v_mov_b64_e32 v[54:55], 0
	v_mov_b64_e32 v[56:57], 0
	v_mov_b64_e32 v[58:59], 0
	v_mov_b64_e32 v[60:61], 0
	v_mov_b64_e32 v[62:63], 0
	v_mov_b64_e32 v[64:65], 0
	v_mov_b64_e32 v[66:67], 0
	v_mov_b64_e32 v[68:69], 0
	v_mov_b64_e32 v[70:71], 0
	v_mov_b64_e32 v[72:73], 0
	v_mov_b64_e32 v[74:75], 0
	v_mov_b64_e32 v[76:77], 0
	v_mov_b64_e32 v[78:79], 0
	v_mov_b64_e32 v[88:89], 0
	v_mov_b64_e32 v[90:91], 0
	v_mov_b64_e32 v[92:93], 0
	v_mov_b64_e32 v[94:95], 0
	v_mov_b64_e32 v[104:105], 0
	v_mov_b64_e32 v[106:107], 0
	v_mov_b64_e32 v[108:109], 0
	v_mov_b64_e32 v[110:111], 0
	v_mov_b64_e32 v[80:81], 0
	v_mov_b64_e32 v[82:83], 0
	v_mov_b64_e32 v[84:85], 0
	v_mov_b64_e32 v[86:87], 0
	v_mov_b64_e32 v[96:97], 0
	v_mov_b64_e32 v[98:99], 0
	v_mov_b64_e32 v[100:101], 0
	v_mov_b64_e32 v[102:103], 0
	v_mov_b64_e32 v[112:113], 0
	v_mov_b64_e32 v[114:115], 0
	v_mov_b64_e32 v[116:117], 0
	v_mov_b64_e32 v[118:119], 0
	v_mov_b64_e32 v[120:121], 0
	v_mov_b64_e32 v[122:123], 0
	v_mov_b64_e32 v[124:125], 0
	v_mov_b64_e32 v[126:127], 0

; template <class Epi>
; __device__ __forceinline__ void gemm_phase(LAS unsigned char* lds, const Gemm g, const StaticOrder& S, const Epi& E, const int wid) {
;     ...
;         const bool has_next = S.next(ui + 1, nxt);
;         const char* nA = has_next ? (const char*)g.A + (size_t)nxt.pm * tsA : cA; const char* nB = has_next ? (const char*)g.Bt + (size_t)nxt.pn * tsB : cB;
; #pragma unroll 1
;         for (int t = 0; t < nt; t += 2) {
;             const bool last = (t == nt - 2);
;             const char* a1 = cA + (size_t)(t + 1) * kstep;
;             const char* a2 = last ? nA : cA + (size_t)(t + 2) * kstep; const char* b2 = last ? nB : cB + (size_t)(t + 2) * kstep;
;             const char* a3 = a2 + kstep; const char* b3 = b2 + kstep;
;     ...
; #pragma unroll
;         for (int a = 0; a < 2; ++a)
; #pragma unroll
;             for (int b = 0; b < 2; ++b)
; #pragma unroll
;                 for (int m = 0; m < 4; ++m)
; #pragma unroll
;                     for (int n = 0; n < 2; ++n) acc[a][b][m][n] = (f32x4){0.f, 0.f, 0.f, 0.f};
.LBB0_888:
	s_ashr_i32 s19, s18, 31
	s_lshl_b64 s[4:5], s[18:19], 17
	s_add_u32 s22, s66, s4
	s_addc_u32 s23, s67, s5
	s_and_b64 s[4:5], s[8:9], exec
	v_mov_b64_e32 v[0:1], 0
	s_cselect_b32 s19, s23, s25
	s_cselect_b32 s97, s22, s24
	s_mov_b32 s30, 0
	s_mov_b64 s[8:9], -1
	s_mov_b64 s[28:29], 0
	v_mov_b64_e32 v[2:3], 0
	v_mov_b64_e32 v[4:5], 0
	v_mov_b64_e32 v[6:7], 0
	v_mov_b64_e32 v[8:9], 0
	v_mov_b64_e32 v[10:11], 0
	v_mov_b64_e32 v[16:17], 0
	v_mov_b64_e32 v[18:19], 0
	v_mov_b64_e32 v[24:25], 0
	v_mov_b64_e32 v[26:27], 0
	v_mov_b64_e32 v[32:33], 0
	v_mov_b64_e32 v[34:35], 0
	v_mov_b64_e32 v[40:41], 0
	v_mov_b64_e32 v[42:43], 0
	v_mov_b64_e32 v[48:49], 0
	v_mov_b64_e32 v[50:51], 0
	v_mov_b64_e32 v[12:13], 0
	v_mov_b64_e32 v[14:15], 0
	v_mov_b64_e32 v[20:21], 0
	v_mov_b64_e32 v[22:23], 0
	v_mov_b64_e32 v[28:29], 0
	v_mov_b64_e32 v[30:31], 0
	v_mov_b64_e32 v[36:37], 0
	v_mov_b64_e32 v[38:39], 0
	v_mov_b64_e32 v[44:45], 0
	v_mov_b64_e32 v[46:47], 0
	v_mov_b64_e32 v[52:53], 0
	v_mov_b64_e32 v[54:55], 0
	v_mov_b64_e32 v[56:57], 0
	v_mov_b64_e32 v[58:59], 0
	v_mov_b64_e32 v[60:61], 0
	v_mov_b64_e32 v[62:63], 0
	v_mov_b64_e32 v[64:65], 0
	v_mov_b64_e32 v[66:67], 0
	v_mov_b64_e32 v[68:69], 0
	v_mov_b64_e32 v[70:71], 0
	v_mov_b64_e32 v[80:81], 0
	v_mov_b64_e32 v[82:83], 0
	v_mov_b64_e32 v[84:85], 0
	v_mov_b64_e32 v[86:87], 0
	v_mov_b64_e32 v[88:89], 0
	v_mov_b64_e32 v[90:91], 0
	v_mov_b64_e32 v[92:93], 0
	v_mov_b64_e32 v[94:95], 0
	v_mov_b64_e32 v[96:97], 0
	v_mov_b64_e32 v[98:99], 0
	v_mov_b64_e32 v[104:105], 0
	v_mov_b64_e32 v[106:107], 0
	v_mov_b64_e32 v[72:73], 0
	v_mov_b64_e32 v[74:75], 0
	v_mov_b64_e32 v[76:77], 0
	v_mov_b64_e32 v[78:79], 0
	v_mov_b64_e32 v[100:101], 0
	v_mov_b64_e32 v[102:103], 0
	v_mov_b64_e32 v[108:109], 0
	v_mov_b64_e32 v[110:111], 0
	v_mov_b64_e32 v[112:113], 0
	v_mov_b64_e32 v[114:115], 0
	v_mov_b64_e32 v[116:117], 0
	v_mov_b64_e32 v[118:119], 0
	v_mov_b64_e32 v[120:121], 0
	v_mov_b64_e32 v[122:123], 0
	v_mov_b64_e32 v[124:125], 0
	v_mov_b64_e32 v[126:127], 0

; template <class Epi>
; __device__ __forceinline__ void gemm_phase(LAS unsigned char* lds, const Gemm g, const StaticOrder& S, const Epi& E, const int wid) {
;     ...
;         const bool has_next = S.next(ui + 1, nxt);
;         const char* nA = has_next ? (const char*)g.A + (size_t)nxt.pm * tsA : cA; const char* nB = has_next ? (const char*)g.Bt + (size_t)nxt.pn * tsB : cB;
; #pragma unroll 1
;         for (int t = 0; t < nt; t += 2) {
;             const bool last = (t == nt - 2);
;             const char* a1 = cA + (size_t)(t + 1) * kstep;
;             const char* a2 = last ? nA : cA + (size_t)(t + 2) * kstep; const char* b2 = last ? nB : cB + (size_t)(t + 2) * kstep;
;             const char* a3 = a2 + kstep; const char* b3 = b2 + kstep;
;     ...
; #pragma unroll
;         for (int a = 0; a < 2; ++a)
; #pragma unroll
;             for (int b = 0; b < 2; ++b)
; #pragma unroll
;                 for (int m = 0; m < 4; ++m)
; #pragma unroll
;                     for (int n = 0; n < 2; ++n) acc[a][b][m][n] = (f32x4){0.f, 0.f, 0.f, 0.f};
.LBB0_1090:
	s_ashr_i32 s21, s20, 31
	s_lshl_b64 s[4:5], s[20:21], 19
	s_add_u32 s22, s44, s4
	s_addc_u32 s23, s45, s5
	s_and_b64 s[4:5], s[6:7], exec
	s_cselect_b32 s1, s23, s31
	s_cselect_b32 s21, s22, s30
	s_ashr_i32 s19, s18, 31
	s_lshl_b64 s[4:5], s[18:19], 19
	s_add_u32 s24, s36, s4
	s_addc_u32 s25, s37, s5
	s_and_b64 s[4:5], s[6:7], exec
	s_cselect_b32 s19, s25, s29
	s_cselect_b32 s66, s24, s28
	s_add_u32 s67, s28, 0x100
	s_addc_u32 s73, s29, 0
	s_add_u32 s28, s30, 0x40080
	v_mov_b32_e32 v0, 0
	s_addc_u32 s29, s31, 0
	s_mov_b32 s74, -2
	s_waitcnt lgkmcnt(0)
	v_mov_b32_e32 v1, v0
	v_mov_b64_e32 v[2:3], 0
	v_mov_b64_e32 v[4:5], 0
	v_mov_b64_e32 v[6:7], 0
	v_mov_b64_e32 v[16:17], 0
	v_mov_b64_e32 v[18:19], 0
	v_mov_b64_e32 v[20:21], 0
	v_mov_b64_e32 v[22:23], 0
	v_mov_b64_e32 v[32:33], 0
	v_mov_b64_e32 v[34:35], 0
	v_mov_b64_e32 v[36:37], 0
	v_mov_b64_e32 v[38:39], 0
	v_mov_b64_e32 v[48:49], 0
	v_mov_b64_e32 v[50:51], 0
	v_mov_b64_e32 v[52:53], 0
	v_mov_b64_e32 v[54:55], 0
	v_mov_b64_e32 v[8:9], 0
	v_mov_b64_e32 v[10:11], 0
	v_mov_b64_e32 v[12:13], 0
	v_mov_b64_e32 v[14:15], 0
	v_mov_b64_e32 v[24:25], 0
	v_mov_b64_e32 v[26:27], 0
	v_mov_b64_e32 v[28:29], 0
	v_mov_b64_e32 v[30:31], 0
	v_mov_b64_e32 v[40:41], 0
	v_mov_b64_e32 v[42:43], 0
	v_mov_b64_e32 v[44:45], 0
	v_mov_b64_e32 v[46:47], 0
	v_mov_b64_e32 v[56:57], 0
	v_mov_b64_e32 v[58:59], 0
	v_mov_b64_e32 v[60:61], 0
	v_mov_b64_e32 v[62:63], 0
	v_mov_b64_e32 v[64:65], 0
	v_mov_b64_e32 v[66:67], 0
	v_mov_b64_e32 v[68:69], 0
	v_mov_b64_e32 v[70:71], 0
	v_mov_b64_e32 v[80:81], 0
	v_mov_b64_e32 v[82:83], 0
	v_mov_b64_e32 v[84:85], 0
	v_mov_b64_e32 v[86:87], 0
	v_mov_b64_e32 v[96:97], 0
	v_mov_b64_e32 v[98:99], 0
	v_mov_b64_e32 v[100:101], 0
	v_mov_b64_e32 v[102:103], 0
	v_mov_b64_e32 v[112:113], 0
	v_mov_b64_e32 v[114:115], 0
	v_mov_b64_e32 v[116:117], 0
	v_mov_b64_e32 v[118:119], 0
	v_mov_b64_e32 v[72:73], 0
	v_mov_b64_e32 v[74:75], 0
	v_mov_b64_e32 v[76:77], 0
	v_mov_b64_e32 v[78:79], 0
	v_mov_b64_e32 v[88:89], 0
	v_mov_b64_e32 v[90:91], 0
	v_mov_b64_e32 v[92:93], 0
	v_mov_b64_e32 v[94:95], 0
	v_mov_b64_e32 v[104:105], 0
	v_mov_b64_e32 v[106:107], 0
	v_mov_b64_e32 v[108:109], 0
	v_mov_b64_e32 v[110:111], 0
	v_mov_b64_e32 v[128:129], 0
	v_mov_b64_e32 v[130:131], 0
	v_mov_b64_e32 v[140:141], 0
	v_mov_b64_e32 v[142:143], 0

; template <class Epi>
; __device__ __forceinline__ void gemm_phase(LAS unsigned char* lds, const Gemm g, const StaticOrder& S, const Epi& E, const int wid) {
;     ...
;         const bool has_next = S.next(ui + 1, nxt);
;         const char* nA = has_next ? (const char*)g.A + (size_t)nxt.pm * tsA : cA; const char* nB = has_next ? (const char*)g.Bt + (size_t)nxt.pn * tsB : cB;
; #pragma unroll 1
;         for (int t = 0; t < nt; t += 2) {
;             const bool last = (t == nt - 2);
;             const char* a1 = cA + (size_t)(t + 1) * kstep;
;             const char* a2 = last ? nA : cA + (size_t)(t + 2) * kstep; const char* b2 = last ? nB : cB + (size_t)(t + 2) * kstep;
;             const char* a3 = a2 + kstep; const char* b3 = b2 + kstep;
;     ...
; #pragma unroll
;         for (int a = 0; a < 2; ++a)
; #pragma unroll
;             for (int b = 0; b < 2; ++b)
; #pragma unroll
;                 for (int m = 0; m < 4; ++m)
; #pragma unroll
;                     for (int n = 0; n < 2; ++n) acc[a][b][m][n] = (f32x4){0.f, 0.f, 0.f, 0.f};
.LBB0_1174:
	s_ashr_i32 s25, s24, 31
	s_lshl_b64 s[26:27], s[24:25], 19
	s_add_u32 s26, s42, s26
	s_addc_u32 s27, s43, s27
	s_and_b64 s[28:29], s[4:5], exec
	s_cselect_b32 s25, s27, s37
	s_cselect_b32 s80, s26, s36
	s_ashr_i32 s23, s22, 31
	s_lshl_b64 s[28:29], s[22:23], 19
	s_add_u32 s28, s51, s28
	s_addc_u32 s29, s58, s29
	s_and_b64 s[38:39], s[4:5], exec
	s_cselect_b32 s23, s29, s35
	s_cselect_b32 s81, s28, s34
	s_add_u32 s82, s34, 0x100
	s_addc_u32 s83, s35, 0
	s_add_u32 s34, s36, 0x40080
	v_mov_b64_e32 v[0:1], 0
	s_addc_u32 s35, s37, 0
	s_mov_b32 s87, -2
	v_mov_b64_e32 v[2:3], 0
	v_mov_b64_e32 v[4:5], 0
	v_mov_b64_e32 v[6:7], 0
	v_mov_b64_e32 v[16:17], 0
	v_mov_b64_e32 v[18:19], 0
	v_mov_b64_e32 v[20:21], 0
	v_mov_b64_e32 v[22:23], 0
	v_mov_b64_e32 v[32:33], 0
	v_mov_b64_e32 v[34:35], 0
	v_mov_b64_e32 v[36:37], 0
	v_mov_b64_e32 v[38:39], 0
	v_mov_b64_e32 v[48:49], 0
	v_mov_b64_e32 v[50:51], 0
	v_mov_b64_e32 v[52:53], 0
	v_mov_b64_e32 v[54:55], 0
	v_mov_b64_e32 v[8:9], 0
	v_mov_b64_e32 v[10:11], 0
	v_mov_b64_e32 v[12:13], 0
	v_mov_b64_e32 v[14:15], 0
	v_mov_b64_e32 v[24:25], 0
	v_mov_b64_e32 v[26:27], 0
	v_mov_b64_e32 v[28:29], 0
	v_mov_b64_e32 v[30:31], 0
	v_mov_b64_e32 v[40:41], 0
	v_mov_b64_e32 v[42:43], 0
	v_mov_b64_e32 v[44:45], 0
	v_mov_b64_e32 v[46:47], 0
	v_mov_b64_e32 v[56:57], 0
	v_mov_b64_e32 v[58:59], 0
	v_mov_b64_e32 v[60:61], 0
	v_mov_b64_e32 v[62:63], 0
	v_mov_b64_e32 v[64:65], 0
	v_mov_b64_e32 v[66:67], 0
	v_mov_b64_e32 v[68:69], 0
	v_mov_b64_e32 v[70:71], 0
	v_mov_b64_e32 v[80:81], 0
	v_mov_b64_e32 v[82:83], 0
	v_mov_b64_e32 v[84:85], 0
	v_mov_b64_e32 v[86:87], 0
	v_mov_b64_e32 v[96:97], 0
	v_mov_b64_e32 v[98:99], 0
	v_mov_b64_e32 v[100:101], 0
	v_mov_b64_e32 v[102:103], 0
	v_mov_b64_e32 v[112:113], 0
	v_mov_b64_e32 v[114:115], 0
	v_mov_b64_e32 v[116:117], 0
	v_mov_b64_e32 v[118:119], 0
	v_mov_b64_e32 v[72:73], 0
	v_mov_b64_e32 v[74:75], 0
	v_mov_b64_e32 v[76:77], 0
	v_mov_b64_e32 v[78:79], 0
	v_mov_b64_e32 v[88:89], 0
	v_mov_b64_e32 v[90:91], 0
	v_mov_b64_e32 v[92:93], 0
	v_mov_b64_e32 v[94:95], 0
	v_mov_b64_e32 v[104:105], 0
	v_mov_b64_e32 v[106:107], 0
	v_mov_b64_e32 v[108:109], 0
	v_mov_b64_e32 v[110:111], 0
	v_mov_b64_e32 v[120:121], 0
	v_mov_b64_e32 v[122:123], 0
	v_mov_b64_e32 v[124:125], 0
	v_mov_b64_e32 v[126:127], 0

; template <class Epi>
; __device__ __forceinline__ void gemm_phase(LAS unsigned char* lds, const Gemm g, const StaticOrder& S, const Epi& E, const int wid) {
;     ...
;         const bool has_next = S.next(ui + 1, nxt);
;         const char* nA = has_next ? (const char*)g.A + (size_t)nxt.pm * tsA : cA; const char* nB = has_next ? (const char*)g.Bt + (size_t)nxt.pn * tsB : cB;
; #pragma unroll 1
;         for (int t = 0; t < nt; t += 2) {
;             const bool last = (t == nt - 2);
;             const char* a1 = cA + (size_t)(t + 1) * kstep;
;             const char* a2 = last ? nA : cA + (size_t)(t + 2) * kstep; const char* b2 = last ? nB : cB + (size_t)(t + 2) * kstep;
;             const char* a3 = a2 + kstep; const char* b3 = b2 + kstep;
;     ...
; #pragma unroll
;         for (int a = 0; a < 2; ++a)
; #pragma unroll
;             for (int b = 0; b < 2; ++b)
; #pragma unroll
;                 for (int m = 0; m < 4; ++m)
; #pragma unroll
;                     for (int n = 0; n < 2; ++n) acc[a][b][m][n] = (f32x4){0.f, 0.f, 0.f, 0.f};
.LBB0_1244:
	s_ashr_i32 s19, s18, 31
	s_lshl_b64 s[20:21], s[18:19], 21
	s_add_u32 s20, s44, s20
	s_addc_u32 s21, s45, s21
	s_and_b64 s[22:23], s[4:5], exec
	s_cselect_b32 s1, s21, s29
	s_cselect_b32 s19, s20, s28
	s_ashr_i32 s17, s16, 31
	s_lshl_b64 s[22:23], s[16:17], 21
	s_add_u32 s22, s34, s22
	s_addc_u32 s23, s35, s23
	s_and_b64 s[30:31], s[4:5], exec
	s_cselect_b32 s17, s23, s27
	s_cselect_b32 s66, s22, s26
	s_add_u32 s67, s26, 0x100
	s_addc_u32 s73, s27, 0
	s_add_u32 s26, s28, 0x100080
	v_mov_b32_e32 v0, 0
	s_addc_u32 s27, s29, 0
	s_mov_b32 s74, -2
	v_mov_b32_e32 v1, v0
	v_mov_b64_e32 v[2:3], 0
	v_mov_b64_e32 v[4:5], 0
	v_mov_b64_e32 v[6:7], 0
	v_mov_b64_e32 v[16:17], 0
	v_mov_b64_e32 v[18:19], 0
	v_mov_b64_e32 v[20:21], 0
	v_mov_b64_e32 v[22:23], 0
	v_mov_b64_e32 v[32:33], 0
	v_mov_b64_e32 v[34:35], 0
	v_mov_b64_e32 v[36:37], 0
	v_mov_b64_e32 v[38:39], 0
	v_mov_b64_e32 v[48:49], 0
	v_mov_b64_e32 v[50:51], 0
	v_mov_b64_e32 v[52:53], 0
	v_mov_b64_e32 v[54:55], 0
	v_mov_b64_e32 v[8:9], 0
	v_mov_b64_e32 v[10:11], 0
	v_mov_b64_e32 v[12:13], 0
	v_mov_b64_e32 v[14:15], 0
	v_mov_b64_e32 v[24:25], 0
	v_mov_b64_e32 v[26:27], 0
	v_mov_b64_e32 v[28:29], 0
	v_mov_b64_e32 v[30:31], 0
	v_mov_b64_e32 v[40:41], 0
	v_mov_b64_e32 v[42:43], 0
	v_mov_b64_e32 v[44:45], 0
	v_mov_b64_e32 v[46:47], 0
	v_mov_b64_e32 v[56:57], 0
	v_mov_b64_e32 v[58:59], 0
	v_mov_b64_e32 v[60:61], 0
	v_mov_b64_e32 v[62:63], 0
	v_mov_b64_e32 v[64:65], 0
	v_mov_b64_e32 v[66:67], 0
	v_mov_b64_e32 v[68:69], 0
	v_mov_b64_e32 v[70:71], 0
	v_mov_b64_e32 v[80:81], 0
	v_mov_b64_e32 v[82:83], 0
	v_mov_b64_e32 v[84:85], 0
	v_mov_b64_e32 v[86:87], 0
	v_mov_b64_e32 v[96:97], 0
	v_mov_b64_e32 v[98:99], 0
	v_mov_b64_e32 v[100:101], 0
	v_mov_b64_e32 v[102:103], 0
	v_mov_b64_e32 v[112:113], 0
	v_mov_b64_e32 v[114:115], 0
	v_mov_b64_e32 v[116:117], 0
	v_mov_b64_e32 v[118:119], 0
	v_mov_b64_e32 v[72:73], 0
	v_mov_b64_e32 v[74:75], 0
	v_mov_b64_e32 v[76:77], 0
	v_mov_b64_e32 v[78:79], 0
	v_mov_b64_e32 v[88:89], 0
	v_mov_b64_e32 v[90:91], 0
	v_mov_b64_e32 v[92:93], 0
	v_mov_b64_e32 v[94:95], 0
	v_mov_b64_e32 v[104:105], 0
	v_mov_b64_e32 v[106:107], 0
	v_mov_b64_e32 v[108:109], 0
	v_mov_b64_e32 v[110:111], 0
	v_mov_b64_e32 v[120:121], 0
	v_mov_b64_e32 v[122:123], 0
	v_mov_b64_e32 v[128:129], 0
	v_mov_b64_e32 v[130:131], 0

; template <class Epi>
; __device__ __forceinline__ void gemm_phase(LAS unsigned char* lds, const Gemm g, const StaticOrder& S, const Epi& E, const int wid) {
;     ...
;         const bool has_next = S.next(ui + 1, nxt);
;         const char* nA = has_next ? (const char*)g.A + (size_t)nxt.pm * tsA : cA; const char* nB = has_next ? (const char*)g.Bt + (size_t)nxt.pn * tsB : cB;
; #pragma unroll 1
;         for (int t = 0; t < nt; t += 2) {
;             const bool last = (t == nt - 2);
;             const char* a1 = cA + (size_t)(t + 1) * kstep;
;             const char* a2 = last ? nA : cA + (size_t)(t + 2) * kstep; const char* b2 = last ? nB : cB + (size_t)(t + 2) * kstep;
;             const char* a3 = a2 + kstep; const char* b3 = b2 + kstep;
;     ...
; #pragma unroll
;         for (int a = 0; a < 2; ++a)
; #pragma unroll
;             for (int b = 0; b < 2; ++b)
; #pragma unroll
;                 for (int m = 0; m < 4; ++m)
; #pragma unroll
;                     for (int n = 0; n < 2; ++n) acc[a][b][m][n] = (f32x4){0.f, 0.f, 0.f, 0.f};
.LBB0_1328:
	s_ashr_i32 s25, s24, 31
	s_lshl_b64 s[30:31], s[24:25], 17
	s_add_u32 s30, s64, s30
	s_addc_u32 s31, s65, s31
	s_and_b64 s[34:35], s[0:1], exec
	s_cselect_b32 s25, s31, s29
	s_cselect_b32 s88, s30, s28
	s_ashr_i32 s23, s22, 31
	s_lshl_b64 s[34:35], s[22:23], 17
	s_add_u32 s34, s66, s34
	s_addc_u32 s35, s67, s35
	s_and_b64 s[38:39], s[0:1], exec
	v_mov_b64_e32 v[0:1], 0
	s_cselect_b32 s23, s35, s27
	s_cselect_b32 s89, s34, s26
	s_mov_b64 s[46:47], 0
	s_mov_b64 s[38:39], -1
	s_mov_b64 s[44:45], 0
	v_mov_b64_e32 v[2:3], 0
	v_mov_b64_e32 v[4:5], 0
	v_mov_b64_e32 v[6:7], 0
	v_mov_b64_e32 v[8:9], 0
	v_mov_b64_e32 v[10:11], 0
	v_mov_b64_e32 v[12:13], 0
	v_mov_b64_e32 v[14:15], 0
	v_mov_b64_e32 v[24:25], 0
	v_mov_b64_e32 v[26:27], 0
	v_mov_b64_e32 v[28:29], 0
	v_mov_b64_e32 v[30:31], 0
	v_mov_b64_e32 v[40:41], 0
	v_mov_b64_e32 v[42:43], 0
	v_mov_b64_e32 v[44:45], 0
	v_mov_b64_e32 v[46:47], 0
	v_mov_b64_e32 v[16:17], 0
	v_mov_b64_e32 v[18:19], 0
	v_mov_b64_e32 v[20:21], 0
	v_mov_b64_e32 v[22:23], 0
	v_mov_b64_e32 v[32:33], 0
	v_mov_b64_e32 v[34:35], 0
	v_mov_b64_e32 v[36:37], 0
	v_mov_b64_e32 v[38:39], 0
	v_mov_b64_e32 v[48:49], 0
	v_mov_b64_e32 v[50:51], 0
	v_mov_b64_e32 v[52:53], 0
	v_mov_b64_e32 v[54:55], 0
	v_mov_b64_e32 v[56:57], 0
	v_mov_b64_e32 v[58:59], 0
	v_mov_b64_e32 v[60:61], 0
	v_mov_b64_e32 v[62:63], 0
	v_mov_b64_e32 v[64:65], 0
	v_mov_b64_e32 v[66:67], 0
	v_mov_b64_e32 v[68:69], 0
	v_mov_b64_e32 v[70:71], 0
	v_mov_b64_e32 v[72:73], 0
	v_mov_b64_e32 v[74:75], 0
	v_mov_b64_e32 v[76:77], 0
	v_mov_b64_e32 v[78:79], 0
	v_mov_b64_e32 v[88:89], 0
	v_mov_b64_e32 v[90:91], 0
	v_mov_b64_e32 v[92:93], 0
	v_mov_b64_e32 v[94:95], 0
	v_mov_b64_e32 v[104:105], 0
	v_mov_b64_e32 v[106:107], 0
	v_mov_b64_e32 v[108:109], 0
	v_mov_b64_e32 v[110:111], 0
	v_mov_b64_e32 v[80:81], 0
	v_mov_b64_e32 v[82:83], 0
	v_mov_b64_e32 v[84:85], 0
	v_mov_b64_e32 v[86:87], 0
	v_mov_b64_e32 v[96:97], 0
	v_mov_b64_e32 v[98:99], 0
	v_mov_b64_e32 v[100:101], 0
	v_mov_b64_e32 v[102:103], 0
	v_mov_b64_e32 v[112:113], 0
	v_mov_b64_e32 v[114:115], 0
	v_mov_b64_e32 v[116:117], 0
	v_mov_b64_e32 v[118:119], 0
	v_mov_b64_e32 v[120:121], 0
	v_mov_b64_e32 v[122:123], 0
	v_mov_b64_e32 v[124:125], 0
	v_mov_b64_e32 v[126:127], 0

; template <class Epi>
; __device__ __forceinline__ void gemm_phase(LAS unsigned char* lds, const Gemm g, const StaticOrder& S, const Epi& E, const int wid) {
;     ...
;         const bool has_next = S.next(ui + 1, nxt);
;         const char* nA = has_next ? (const char*)g.A + (size_t)nxt.pm * tsA : cA; const char* nB = has_next ? (const char*)g.Bt + (size_t)nxt.pn * tsB : cB;
; #pragma unroll 1
;         for (int t = 0; t < nt; t += 2) {
;             const bool last = (t == nt - 2);
;             const char* a1 = cA + (size_t)(t + 1) * kstep;
;             const char* a2 = last ? nA : cA + (size_t)(t + 2) * kstep; const char* b2 = last ? nB : cB + (size_t)(t + 2) * kstep;
;             const char* a3 = a2 + kstep; const char* b3 = b2 + kstep;
;     ...
; #pragma unroll
;         for (int a = 0; a < 2; ++a)
; #pragma unroll
;             for (int b = 0; b < 2; ++b)
; #pragma unroll
;                 for (int m = 0; m < 4; ++m)
; #pragma unroll
;                     for (int n = 0; n < 2; ++n) acc[a][b][m][n] = (f32x4){0.f, 0.f, 0.f, 0.f};
.LBB0_1352:
	s_ashr_i32 s23, s22, 31
	s_lshl_b64 s[24:25], s[22:23], 19
	s_add_u32 s24, s42, s24
	s_addc_u32 s25, s43, s25
	s_and_b64 s[26:27], s[0:1], exec
	s_cselect_b32 s23, s25, s35
	s_cselect_b32 s61, s24, s34
	s_ashr_i32 s21, s20, 31
	s_lshl_b64 s[26:27], s[20:21], 19
	s_add_u32 s26, s45, s26
	s_addc_u32 s27, s46, s27
	s_and_b64 s[38:39], s[0:1], exec
	s_cselect_b32 s21, s27, s31
	s_cselect_b32 s62, s26, s30
	s_add_u32 s63, s30, 0x100
	s_addc_u32 s64, s31, 0
	s_add_u32 s30, s34, 0x40080
	v_mov_b32_e32 v4, 0
	s_addc_u32 s31, s35, 0
	s_mov_b32 s65, -2
	v_mov_b32_e32 v5, v4
	v_mov_b64_e32 v[6:7], 0
	v_mov_b64_e32 v[0:1], 0
	v_mov_b64_e32 v[2:3], 0
	v_mov_b64_e32 v[20:21], 0
	v_mov_b64_e32 v[22:23], 0
	v_mov_b64_e32 v[16:17], 0
	v_mov_b64_e32 v[18:19], 0
	v_mov_b64_e32 v[36:37], 0
	v_mov_b64_e32 v[38:39], 0
	v_mov_b64_e32 v[32:33], 0
	v_mov_b64_e32 v[34:35], 0
	v_mov_b64_e32 v[52:53], 0
	v_mov_b64_e32 v[54:55], 0
	v_mov_b64_e32 v[48:49], 0
	v_mov_b64_e32 v[50:51], 0
	v_mov_b64_e32 v[12:13], 0
	v_mov_b64_e32 v[14:15], 0
	v_mov_b64_e32 v[8:9], 0
	v_mov_b64_e32 v[10:11], 0
	v_mov_b64_e32 v[28:29], 0
	v_mov_b64_e32 v[30:31], 0
	v_mov_b64_e32 v[24:25], 0
	v_mov_b64_e32 v[26:27], 0
	v_mov_b64_e32 v[44:45], 0
	v_mov_b64_e32 v[46:47], 0
	v_mov_b64_e32 v[40:41], 0
	v_mov_b64_e32 v[42:43], 0
	v_mov_b64_e32 v[60:61], 0
	v_mov_b64_e32 v[62:63], 0
	v_mov_b64_e32 v[56:57], 0
	v_mov_b64_e32 v[58:59], 0
	v_mov_b64_e32 v[68:69], 0
	v_mov_b64_e32 v[70:71], 0
	v_mov_b64_e32 v[64:65], 0
	v_mov_b64_e32 v[66:67], 0
	v_mov_b64_e32 v[84:85], 0
	v_mov_b64_e32 v[86:87], 0
	v_mov_b64_e32 v[80:81], 0
	v_mov_b64_e32 v[82:83], 0
	v_mov_b64_e32 v[100:101], 0
	v_mov_b64_e32 v[102:103], 0
	v_mov_b64_e32 v[96:97], 0
	v_mov_b64_e32 v[98:99], 0
	v_mov_b64_e32 v[116:117], 0
	v_mov_b64_e32 v[118:119], 0
	v_mov_b64_e32 v[112:113], 0
	v_mov_b64_e32 v[114:115], 0
	v_mov_b64_e32 v[76:77], 0
	v_mov_b64_e32 v[78:79], 0
	v_mov_b64_e32 v[72:73], 0
	v_mov_b64_e32 v[74:75], 0
	v_mov_b64_e32 v[92:93], 0
	v_mov_b64_e32 v[94:95], 0
	v_mov_b64_e32 v[88:89], 0
	v_mov_b64_e32 v[90:91], 0
	v_mov_b64_e32 v[108:109], 0
	v_mov_b64_e32 v[110:111], 0
	v_mov_b64_e32 v[104:105], 0
	v_mov_b64_e32 v[106:107], 0
	v_mov_b64_e32 v[120:121], 0
	v_mov_b64_e32 v[122:123], 0
	v_mov_b64_e32 v[124:125], 0
	v_mov_b64_e32 v[126:127], 0
